# GEMM epilogues (SwiGLU, projection, K/V head-norm): row-scale LDS reads hoisted to the top of the epilogue block
# baseline (speedup 1.0000x reference)
.LBB0_44:
	s_lshl_b32 s15, s64, 10
	s_and_b32 s15, s15, 0x1c00
	v_add_u32_e32 v147, s15, v143
	ds_read2_b32 v[154:155], v147 offset1:16
	ds_read2_b32 v[156:157], v147 offset0:32 offset1:48
	ds_read2_b32 v[158:159], v147 offset0:128 offset1:144
	s_nop 0
	v_pk_mul_f32 v[122:123], v[118:119], v[122:123]
	v_pk_mul_f32 v[130:131], v[126:127], v[130:131]
	v_lshl_add_u32 v146, s64, 8, v3
	v_lshl_or_b32 v140, s65, 7, v144
	s_nop 0
	s_waitcnt lgkmcnt(2)
	v_mul_f32_e32 v152, 0xbfb8aa3b, v154
	v_mul_f32_e32 v150, v124, v152
	v_mul_f32_e32 v151, v125, v152
	v_exp_f32_e32 v150, v150
	v_exp_f32_e32 v151, v151
	v_mul_f32_e32 v154, v154, v154
	v_pk_mul_f32 v[124:125], v[124:125], v[128:129]
	v_add_f32_e32 v150, 1.0, v150
	v_add_f32_e32 v151, 1.0, v151
	v_rcp_f32_e32 v150, v150
	v_rcp_f32_e32 v151, v151
	v_mul_f32_e32 v118, v118, v152
	v_mul_f32_e32 v119, v119, v152
	v_exp_f32_e32 v118, v118
	v_pk_mul_f32 v[128:129], v[154:155], v[150:151] op_sel_hi:[0,1]
	v_pk_mul_f32 v[124:125], v[124:125], v[128:129]
	v_mul_f32_e32 v128, v116, v152
	v_mul_f32_e32 v129, v117, v152
	v_exp_f32_e32 v128, v128
	v_exp_f32_e32 v129, v129
	v_exp_f32_e32 v119, v119
	v_mul_f32_e32 v126, v126, v152
	v_mul_f32_e32 v127, v127, v152
	v_exp_f32_e32 v126, v126
	v_exp_f32_e32 v127, v127
	v_add_f32_e32 v128, 1.0, v128
	v_add_f32_e32 v129, 1.0, v129
	v_rcp_f32_e32 v128, v128
	v_rcp_f32_e32 v129, v129
	v_add_f32_e32 v118, 1.0, v118
	v_add_f32_e32 v119, 1.0, v119
	v_rcp_f32_e32 v118, v118
	v_rcp_f32_e32 v119, v119
	v_add_f32_e32 v126, 1.0, v126
	v_add_f32_e32 v127, 1.0, v127
	v_rcp_f32_e32 v126, v126
	v_rcp_f32_e32 v127, v127
	v_pk_mul_f32 v[116:117], v[116:117], v[120:121]
	v_pk_mul_f32 v[120:121], v[154:155], v[128:129] op_sel_hi:[0,1]
	v_pk_mul_f32 v[116:117], v[116:117], v[120:121]
	v_pk_mul_f32 v[118:119], v[154:155], v[118:119] op_sel_hi:[0,1]
	v_pk_mul_f32 v[118:119], v[122:123], v[118:119]
	v_cvt_pk_bf16_f32 v122, v116, v117
	v_mov_b64_e32 v[116:117], s[4:5]
	s_ashr_i32 s15, s64, 3
	v_ashrrev_i32_e32 v141, 31, v140
	v_pk_mul_f32 v[126:127], v[154:155], v[126:127] op_sel_hi:[0,1]
	v_cvt_pk_bf16_f32 v123, v118, v119
	v_mad_i64_i32 v[118:119], s[36:37], v146, s35, v[116:117]
	v_pk_mul_f32 v[126:127], v[130:131], v[126:127]
	v_cvt_pk_bf16_f32 v120, v124, v125
	v_mad_i64_i32 v[124:125], s[36:37], s15, v215, v[118:119]
	v_lshlrev_b64 v[118:119], 1, v[140:141]
	v_cvt_pk_bf16_f32 v121, v126, v127
	v_lshl_add_u64 v[124:125], v[124:125], 0, v[118:119]
	global_store_dwordx4 v[124:125], v[120:123], off
	v_pk_mul_f32 v[114:115], v[110:111], v[114:115]
	v_pk_mul_f32 v[106:107], v[102:103], v[106:107]
	v_mul_f32_e32 v121, 0xbfb8aa3b, v155
	v_mul_f32_e32 v122, v108, v121
	v_mul_f32_e32 v123, v109, v121
	v_exp_f32_e32 v122, v122
	v_exp_f32_e32 v123, v123
	v_mul_f32_e32 v120, v155, v155
	v_pk_mul_f32 v[108:109], v[108:109], v[112:113]
	v_add_f32_e32 v122, 1.0, v122
	v_add_f32_e32 v123, 1.0, v123
	v_rcp_f32_e32 v122, v122
	v_rcp_f32_e32 v123, v123
	v_mul_f32_e32 v110, v110, v121
	v_mul_f32_e32 v111, v111, v121
	v_exp_f32_e32 v110, v110
	v_pk_mul_f32 v[112:113], v[120:121], v[122:123] op_sel_hi:[0,1]
	v_pk_mul_f32 v[108:109], v[108:109], v[112:113]
	v_mul_f32_e32 v112, v100, v121
	v_mul_f32_e32 v113, v101, v121
	v_exp_f32_e32 v112, v112
	v_exp_f32_e32 v113, v113
	v_pk_mul_f32 v[100:101], v[100:101], v[104:105]
	v_exp_f32_e32 v111, v111
	v_add_f32_e32 v112, 1.0, v112
	v_add_f32_e32 v113, 1.0, v113
	v_rcp_f32_e32 v112, v112
	v_rcp_f32_e32 v113, v113
	v_add_f32_e32 v110, 1.0, v110
	v_add_f32_e32 v111, 1.0, v111
	v_rcp_f32_e32 v110, v110
	v_pk_mul_f32 v[104:105], v[120:121], v[112:113] op_sel_hi:[0,1]
	v_pk_mul_f32 v[104:105], v[100:101], v[104:105]
	v_mul_f32_e32 v100, v102, v121
	v_mul_f32_e32 v101, v103, v121
	v_exp_f32_e32 v100, v100
	v_exp_f32_e32 v101, v101
	v_rcp_f32_e32 v111, v111
	v_or_b32_e32 v112, 16, v146
	v_add_f32_e32 v100, 1.0, v100
	v_add_f32_e32 v101, 1.0, v101
	v_rcp_f32_e32 v100, v100
	v_rcp_f32_e32 v101, v101
	v_pk_mul_f32 v[110:111], v[120:121], v[110:111] op_sel_hi:[0,1]
	v_cvt_pk_bf16_f32 v102, v104, v105
	v_mad_i64_i32 v[104:105], s[36:37], v112, s35, v[116:117]
	v_pk_mul_f32 v[100:101], v[120:121], v[100:101] op_sel_hi:[0,1]
	v_pk_mul_f32 v[110:111], v[114:115], v[110:111]
	v_pk_mul_f32 v[106:107], v[106:107], v[100:101]
	v_mad_i64_i32 v[104:105], s[36:37], s15, v215, v[104:105]
	v_cvt_pk_bf16_f32 v100, v108, v109
	v_cvt_pk_bf16_f32 v101, v110, v111
	v_cvt_pk_bf16_f32 v103, v106, v107
	v_lshl_add_u64 v[104:105], v[104:105], 0, v[118:119]
	global_store_dwordx4 v[104:105], v[100:103], off
	s_nop 0
	v_pk_mul_f32 v[98:99], v[94:95], v[98:99]
	v_pk_mul_f32 v[90:91], v[86:87], v[90:91]
	v_pk_mul_f32 v[82:83], v[78:79], v[82:83]
	v_pk_mul_f32 v[74:75], v[70:71], v[74:75]
	s_nop 0
	s_waitcnt lgkmcnt(1)
	v_mul_f32_e32 v104, 0xbfb8aa3b, v156
	v_mul_f32_e32 v102, v92, v104
	v_mul_f32_e32 v103, v93, v104
	v_exp_f32_e32 v102, v102
	v_exp_f32_e32 v103, v103
	v_mul_f32_e32 v156, v156, v156
	v_pk_mul_f32 v[92:93], v[92:93], v[96:97]
	v_add_f32_e32 v102, 1.0, v102
	v_add_f32_e32 v103, 1.0, v103
	v_rcp_f32_e32 v102, v102
	v_rcp_f32_e32 v103, v103
	v_mul_f32_e32 v94, v94, v104
	v_mul_f32_e32 v95, v95, v104
	v_exp_f32_e32 v94, v94
	v_pk_mul_f32 v[96:97], v[156:157], v[102:103] op_sel_hi:[0,1]
	v_pk_mul_f32 v[92:93], v[92:93], v[96:97]
	v_mul_f32_e32 v96, v84, v104
	v_mul_f32_e32 v97, v85, v104
	v_exp_f32_e32 v96, v96
	v_exp_f32_e32 v97, v97
	v_pk_mul_f32 v[84:85], v[84:85], v[88:89]
	v_exp_f32_e32 v95, v95
	v_add_f32_e32 v96, 1.0, v96
	v_add_f32_e32 v97, 1.0, v97
	v_rcp_f32_e32 v96, v96
	v_rcp_f32_e32 v97, v97
	v_add_f32_e32 v94, 1.0, v94
	v_add_f32_e32 v95, 1.0, v95
	v_rcp_f32_e32 v94, v94
	v_pk_mul_f32 v[88:89], v[156:157], v[96:97] op_sel_hi:[0,1]
	v_pk_mul_f32 v[88:89], v[84:85], v[88:89]
	v_mul_f32_e32 v84, v86, v104
	v_mul_f32_e32 v85, v87, v104
	v_exp_f32_e32 v84, v84
	v_exp_f32_e32 v85, v85
	v_rcp_f32_e32 v95, v95
	v_or_b32_e32 v96, 32, v146
	v_add_f32_e32 v84, 1.0, v84
	v_add_f32_e32 v85, 1.0, v85
	v_rcp_f32_e32 v84, v84
	v_rcp_f32_e32 v85, v85
	v_pk_mul_f32 v[94:95], v[156:157], v[94:95] op_sel_hi:[0,1]
	v_cvt_pk_bf16_f32 v86, v88, v89
	v_mad_i64_i32 v[88:89], s[36:37], v96, s35, v[116:117]
	v_pk_mul_f32 v[84:85], v[156:157], v[84:85] op_sel_hi:[0,1]
	v_pk_mul_f32 v[94:95], v[98:99], v[94:95]
	v_pk_mul_f32 v[90:91], v[90:91], v[84:85]
	v_mad_i64_i32 v[88:89], s[36:37], s15, v215, v[88:89]
	v_cvt_pk_bf16_f32 v84, v92, v93
	v_cvt_pk_bf16_f32 v85, v94, v95
	v_cvt_pk_bf16_f32 v87, v90, v91
	v_lshl_add_u64 v[88:89], v[88:89], 0, v[118:119]
	global_store_dwordx4 v[88:89], v[84:87], off
	v_pk_mul_f32 v[66:67], v[62:63], v[66:67]
	v_pk_mul_f32 v[58:59], v[54:55], v[58:59]
	v_mul_f32_e32 v85, 0xbfb8aa3b, v157
	v_mul_f32_e32 v86, v76, v85
	v_mul_f32_e32 v87, v77, v85
	v_exp_f32_e32 v86, v86
	v_exp_f32_e32 v87, v87
	v_mul_f32_e32 v84, v157, v157
	v_pk_mul_f32 v[76:77], v[76:77], v[80:81]
	v_add_f32_e32 v86, 1.0, v86
	v_add_f32_e32 v87, 1.0, v87
	v_rcp_f32_e32 v86, v86
	v_rcp_f32_e32 v87, v87
	v_mul_f32_e32 v78, v78, v85
	v_mul_f32_e32 v79, v79, v85
	v_exp_f32_e32 v78, v78
	v_pk_mul_f32 v[80:81], v[84:85], v[86:87] op_sel_hi:[0,1]
	v_pk_mul_f32 v[76:77], v[76:77], v[80:81]
	v_mul_f32_e32 v80, v68, v85
	v_mul_f32_e32 v81, v69, v85
	v_exp_f32_e32 v80, v80
	v_exp_f32_e32 v81, v81
	v_pk_mul_f32 v[68:69], v[68:69], v[72:73]
	v_exp_f32_e32 v79, v79
	v_add_f32_e32 v80, 1.0, v80
	v_add_f32_e32 v81, 1.0, v81
	v_rcp_f32_e32 v80, v80
	v_rcp_f32_e32 v81, v81
	v_add_f32_e32 v78, 1.0, v78
	v_add_f32_e32 v79, 1.0, v79
	v_rcp_f32_e32 v78, v78
	v_pk_mul_f32 v[72:73], v[84:85], v[80:81] op_sel_hi:[0,1]
	v_pk_mul_f32 v[72:73], v[68:69], v[72:73]
	v_mul_f32_e32 v68, v70, v85
	v_mul_f32_e32 v69, v71, v85
	v_exp_f32_e32 v68, v68
	v_exp_f32_e32 v69, v69
	v_rcp_f32_e32 v79, v79
	v_or_b32_e32 v80, 48, v146
	v_add_f32_e32 v68, 1.0, v68
	v_add_f32_e32 v69, 1.0, v69
	v_rcp_f32_e32 v68, v68
	v_rcp_f32_e32 v69, v69
	v_pk_mul_f32 v[78:79], v[84:85], v[78:79] op_sel_hi:[0,1]
	v_cvt_pk_bf16_f32 v70, v72, v73
	v_mad_i64_i32 v[72:73], s[36:37], v80, s35, v[116:117]
	v_pk_mul_f32 v[68:69], v[84:85], v[68:69] op_sel_hi:[0,1]
	v_pk_mul_f32 v[78:79], v[82:83], v[78:79]
	v_pk_mul_f32 v[74:75], v[74:75], v[68:69]
	v_mad_i64_i32 v[72:73], s[36:37], s15, v215, v[72:73]
	v_cvt_pk_bf16_f32 v68, v76, v77
	v_cvt_pk_bf16_f32 v69, v78, v79
	v_cvt_pk_bf16_f32 v71, v74, v75
	v_lshl_add_u64 v[72:73], v[72:73], 0, v[118:119]
	global_store_dwordx4 v[72:73], v[68:71], off
	s_nop 0
	v_add_u32_e32 v72, 0x80, v146
	v_pk_mul_f32 v[50:51], v[46:47], v[50:51]
	v_pk_mul_f32 v[42:43], v[38:39], v[42:43]
	v_pk_mul_f32 v[34:35], v[30:31], v[34:35]
	s_nop 0
	s_waitcnt lgkmcnt(0)
	v_mul_f32_e32 v73, 0xbfb8aa3b, v158
	v_mul_f32_e32 v70, v60, v73
	v_mul_f32_e32 v71, v61, v73
	v_exp_f32_e32 v70, v70
	v_exp_f32_e32 v71, v71
	v_mul_f32_e32 v158, v158, v158
	v_pk_mul_f32 v[60:61], v[60:61], v[64:65]
	v_add_f32_e32 v70, 1.0, v70
	v_add_f32_e32 v71, 1.0, v71
	v_rcp_f32_e32 v70, v70
	v_rcp_f32_e32 v71, v71
	v_mul_f32_e32 v62, v62, v73
	v_mul_f32_e32 v63, v63, v73
	v_exp_f32_e32 v62, v62
	v_pk_mul_f32 v[64:65], v[158:159], v[70:71] op_sel_hi:[0,1]
	v_pk_mul_f32 v[60:61], v[60:61], v[64:65]
	v_mul_f32_e32 v64, v52, v73
	v_mul_f32_e32 v65, v53, v73
	v_exp_f32_e32 v64, v64
	v_exp_f32_e32 v65, v65
	v_pk_mul_f32 v[52:53], v[52:53], v[56:57]
	v_exp_f32_e32 v63, v63
	v_add_f32_e32 v64, 1.0, v64
	v_add_f32_e32 v65, 1.0, v65
	v_rcp_f32_e32 v64, v64
	v_rcp_f32_e32 v65, v65
	v_add_f32_e32 v62, 1.0, v62
	v_add_f32_e32 v63, 1.0, v63
	v_rcp_f32_e32 v62, v62
	v_pk_mul_f32 v[56:57], v[158:159], v[64:65] op_sel_hi:[0,1]
	v_pk_mul_f32 v[56:57], v[52:53], v[56:57]
	v_mul_f32_e32 v52, v54, v73
	v_mul_f32_e32 v53, v55, v73
	v_exp_f32_e32 v52, v52
	v_exp_f32_e32 v53, v53
	v_rcp_f32_e32 v63, v63
	v_cvt_pk_bf16_f32 v54, v56, v57
	v_add_f32_e32 v52, 1.0, v52
	v_add_f32_e32 v53, 1.0, v53
	v_rcp_f32_e32 v52, v52
	v_rcp_f32_e32 v53, v53
	v_pk_mul_f32 v[62:63], v[158:159], v[62:63] op_sel_hi:[0,1]
	v_mad_i64_i32 v[56:57], s[36:37], v72, s35, v[116:117]
	v_pk_mul_f32 v[52:53], v[158:159], v[52:53] op_sel_hi:[0,1]
	v_pk_mul_f32 v[62:63], v[66:67], v[62:63]
	v_pk_mul_f32 v[58:59], v[58:59], v[52:53]
	v_mad_i64_i32 v[56:57], s[36:37], s15, v215, v[56:57]
	v_cvt_pk_bf16_f32 v52, v60, v61
	v_cvt_pk_bf16_f32 v53, v62, v63
	v_cvt_pk_bf16_f32 v55, v58, v59
	v_lshl_add_u64 v[56:57], v[56:57], 0, v[118:119]
	global_store_dwordx4 v[56:57], v[52:55], off
	v_pk_mul_f32 v[26:27], v[22:23], v[26:27]
	v_pk_mul_f32 v[4:5], v[8:9], v[4:5]
	v_mul_f32_e32 v53, 0xbfb8aa3b, v159
	v_mul_f32_e32 v54, v44, v53
	v_mul_f32_e32 v55, v45, v53
	v_exp_f32_e32 v54, v54
	v_exp_f32_e32 v55, v55
	v_mul_f32_e32 v52, v159, v159
	v_pk_mul_f32 v[44:45], v[44:45], v[48:49]
	v_add_f32_e32 v54, 1.0, v54
	v_add_f32_e32 v55, 1.0, v55
	v_rcp_f32_e32 v54, v54
	v_rcp_f32_e32 v55, v55
	v_mul_f32_e32 v46, v46, v53
	v_mul_f32_e32 v47, v47, v53
	v_exp_f32_e32 v46, v46
	v_pk_mul_f32 v[48:49], v[52:53], v[54:55] op_sel_hi:[0,1]
	v_pk_mul_f32 v[44:45], v[44:45], v[48:49]
	v_mul_f32_e32 v48, v36, v53
	v_mul_f32_e32 v49, v37, v53
	v_exp_f32_e32 v48, v48
	v_exp_f32_e32 v49, v49
	v_pk_mul_f32 v[36:37], v[36:37], v[40:41]
	v_exp_f32_e32 v47, v47
	v_add_f32_e32 v48, 1.0, v48
	v_add_f32_e32 v49, 1.0, v49
	v_rcp_f32_e32 v48, v48
	v_rcp_f32_e32 v49, v49
	v_add_f32_e32 v46, 1.0, v46
	v_add_f32_e32 v47, 1.0, v47
	v_rcp_f32_e32 v46, v46
	v_pk_mul_f32 v[40:41], v[52:53], v[48:49] op_sel_hi:[0,1]
	v_pk_mul_f32 v[40:41], v[36:37], v[40:41]
	v_mul_f32_e32 v36, v38, v53
	v_mul_f32_e32 v37, v39, v53
	v_exp_f32_e32 v36, v36
	v_exp_f32_e32 v37, v37
	v_rcp_f32_e32 v47, v47
	v_add_u32_e32 v48, 0x90, v146
	v_add_f32_e32 v36, 1.0, v36
	v_add_f32_e32 v37, 1.0, v37
	v_rcp_f32_e32 v36, v36
	v_rcp_f32_e32 v37, v37
	v_pk_mul_f32 v[46:47], v[52:53], v[46:47] op_sel_hi:[0,1]
	v_cvt_pk_bf16_f32 v38, v40, v41
	v_mad_i64_i32 v[40:41], s[36:37], v48, s35, v[116:117]
	v_pk_mul_f32 v[36:37], v[52:53], v[36:37] op_sel_hi:[0,1]
	v_pk_mul_f32 v[46:47], v[50:51], v[46:47]
	v_pk_mul_f32 v[42:43], v[42:43], v[36:37]
	v_mad_i64_i32 v[40:41], s[36:37], s15, v215, v[40:41]
	v_cvt_pk_bf16_f32 v36, v44, v45
	v_cvt_pk_bf16_f32 v37, v46, v47
	v_cvt_pk_bf16_f32 v39, v42, v43
	v_lshl_add_u64 v[40:41], v[40:41], 0, v[118:119]
	global_store_dwordx4 v[40:41], v[36:39], off
	ds_read2_b32 v[36:37], v147 offset0:160 offset1:176
	v_pk_mul_f32 v[18:19], v[14:15], v[18:19]
	v_pk_mul_f32 v[6:7], v[10:11], v[6:7]
	s_waitcnt lgkmcnt(0)
	s_andn2_b64 vcc, exec, s[6:7]
	s_waitcnt lgkmcnt(0)
	v_mul_f32_e32 v40, 0xbfb8aa3b, v36
	v_mul_f32_e32 v38, v28, v40
	v_mul_f32_e32 v39, v29, v40
	v_exp_f32_e32 v38, v38
	v_exp_f32_e32 v39, v39
	v_mul_f32_e32 v36, v36, v36
	v_pk_mul_f32 v[28:29], v[28:29], v[32:33]
	v_add_f32_e32 v38, 1.0, v38
	v_add_f32_e32 v39, 1.0, v39
	v_rcp_f32_e32 v38, v38
	v_rcp_f32_e32 v39, v39
	v_mul_f32_e32 v30, v30, v40
	v_mul_f32_e32 v31, v31, v40
	v_exp_f32_e32 v30, v30
	v_pk_mul_f32 v[32:33], v[36:37], v[38:39] op_sel_hi:[0,1]
	v_pk_mul_f32 v[28:29], v[28:29], v[32:33]
	v_mul_f32_e32 v32, v20, v40
	v_mul_f32_e32 v33, v21, v40
	v_exp_f32_e32 v32, v32
	v_exp_f32_e32 v33, v33
	v_pk_mul_f32 v[20:21], v[20:21], v[24:25]
	v_exp_f32_e32 v31, v31
	v_add_f32_e32 v32, 1.0, v32
	v_add_f32_e32 v33, 1.0, v33
	v_rcp_f32_e32 v32, v32
	v_rcp_f32_e32 v33, v33
	v_add_f32_e32 v30, 1.0, v30
	v_add_f32_e32 v31, 1.0, v31
	v_rcp_f32_e32 v30, v30
	v_pk_mul_f32 v[24:25], v[36:37], v[32:33] op_sel_hi:[0,1]
	v_pk_mul_f32 v[24:25], v[20:21], v[24:25]
	v_mul_f32_e32 v20, v22, v40
	v_mul_f32_e32 v21, v23, v40
	v_exp_f32_e32 v20, v20
	v_exp_f32_e32 v21, v21
	v_rcp_f32_e32 v31, v31
	v_add_u32_e32 v32, 0xa0, v146
	v_add_f32_e32 v20, 1.0, v20
	v_add_f32_e32 v21, 1.0, v21
	v_rcp_f32_e32 v20, v20
	v_rcp_f32_e32 v21, v21
	v_pk_mul_f32 v[30:31], v[36:37], v[30:31] op_sel_hi:[0,1]
	v_cvt_pk_bf16_f32 v22, v24, v25
	v_mad_i64_i32 v[24:25], s[36:37], v32, s35, v[116:117]
	v_pk_mul_f32 v[20:21], v[36:37], v[20:21] op_sel_hi:[0,1]
	v_pk_mul_f32 v[30:31], v[34:35], v[30:31]
	v_pk_mul_f32 v[26:27], v[26:27], v[20:21]
	v_mad_i64_i32 v[24:25], s[36:37], s15, v215, v[24:25]
	v_cvt_pk_bf16_f32 v20, v28, v29
	v_cvt_pk_bf16_f32 v21, v30, v31
	v_cvt_pk_bf16_f32 v23, v26, v27
	v_lshl_add_u64 v[24:25], v[24:25], 0, v[118:119]
	global_store_dwordx4 v[24:25], v[20:23], off
	s_nop 1
	v_mul_f32_e32 v21, 0xbfb8aa3b, v37
	v_mul_f32_e32 v22, v12, v21
	v_mul_f32_e32 v23, v13, v21
	v_exp_f32_e32 v22, v22
	v_exp_f32_e32 v23, v23
	v_mul_f32_e32 v20, v37, v37
	v_pk_mul_f32 v[12:13], v[12:13], v[16:17]
	v_add_f32_e32 v22, 1.0, v22
	v_add_f32_e32 v23, 1.0, v23
	v_rcp_f32_e32 v22, v22
	v_rcp_f32_e32 v23, v23
	v_mul_f32_e32 v14, v14, v21
	v_mul_f32_e32 v15, v15, v21
	v_exp_f32_e32 v14, v14
	v_pk_mul_f32 v[16:17], v[20:21], v[22:23] op_sel_hi:[0,1]
	v_pk_mul_f32 v[12:13], v[12:13], v[16:17]
	v_mul_f32_e32 v16, v8, v21
	v_mul_f32_e32 v17, v9, v21
	v_exp_f32_e32 v16, v16
	v_exp_f32_e32 v17, v17
	v_exp_f32_e32 v15, v15
	v_add_f32_e32 v14, 1.0, v14
	v_add_f32_e32 v16, 1.0, v16
	v_add_f32_e32 v17, 1.0, v17
	v_rcp_f32_e32 v16, v16
	v_rcp_f32_e32 v17, v17
	v_add_f32_e32 v15, 1.0, v15
	v_rcp_f32_e32 v14, v14
	v_rcp_f32_e32 v15, v15
	v_pk_mul_f32 v[8:9], v[20:21], v[16:17] op_sel_hi:[0,1]
	v_pk_mul_f32 v[8:9], v[4:5], v[8:9]
	v_mul_f32_e32 v4, v10, v21
	v_mul_f32_e32 v5, v11, v21
	v_exp_f32_e32 v4, v4
	v_exp_f32_e32 v5, v5
	v_add_u32_e32 v16, 0xb0, v146
	v_pk_mul_f32 v[14:15], v[20:21], v[14:15] op_sel_hi:[0,1]
	v_add_f32_e32 v4, 1.0, v4
	v_add_f32_e32 v5, 1.0, v5
	v_rcp_f32_e32 v4, v4
	v_rcp_f32_e32 v5, v5
	v_pk_mul_f32 v[14:15], v[18:19], v[14:15]
	v_pk_mul_f32 v[4:5], v[20:21], v[4:5] op_sel_hi:[0,1]
	v_pk_mul_f32 v[10:11], v[6:7], v[4:5]
	v_cvt_pk_bf16_f32 v6, v8, v9
	v_mad_i64_i32 v[8:9], s[36:37], v16, s35, v[116:117]
	v_mad_i64_i32 v[8:9], s[36:37], s15, v215, v[8:9]
	v_cvt_pk_bf16_f32 v4, v12, v13
	v_cvt_pk_bf16_f32 v5, v14, v15
	v_cvt_pk_bf16_f32 v7, v10, v11
	v_lshl_add_u64 v[8:9], v[8:9], 0, v[118:119]
	s_mov_b64 s[36:37], -1
	global_store_dwordx4 v[8:9], v[4:7], off
	s_cbranch_vccnz .LBB0_37
	s_andn2_b64 vcc, exec, s[8:9]
	s_cbranch_vccnz .LBB0_36
	s_barrier
	s_branch .LBB0_36

.LBB0_110:
	s_add_i32 s10, 0, 0x20000
	v_add_u32_e32 v174, s10, v161
	ds_read_b128 v[194:197], v174
	s_nop 0
	s_lshl_b32 s11, s50, 8
	v_lshl_or_b32 v182, s48, 8, v177
	v_ashrrev_i32_e32 v183, 31, v182
	s_mov_b64 s[40:41], 0x100000
	s_nop 0
	s_waitcnt lgkmcnt(0)
	v_mov_b32_e32 v174, v195
	v_mov_b32_e32 v175, v196
	v_mov_b32_e32 v195, v197
	v_pk_add_f32 v[174:175], v[174:175], v[194:195]
	s_nop 0
	v_add_f32_e32 v174, v174, v175
	v_fmamk_f32 v174, v174, 0x3b800000, v213
	v_rsq_f32_e32 v184, v174
	v_add_u32_e32 v174, s11, v3
	v_ashrrev_i32_e32 v175, 31, v174
	s_mov_b32 s11, 0x100000
	v_cndmask_b32_e64 v184, 1.0, v184, s[8:9]
	v_mul_f32_e32 v172, v172, v184
	v_pk_mul_f32 v[128:129], v[128:129], v[172:173] op_sel_hi:[1,0]
	v_pk_mul_f32 v[130:131], v[130:131], v[172:173] op_sel_hi:[1,0]
	v_pk_mul_f32 v[124:125], v[124:125], v[172:173] op_sel_hi:[1,0]
	s_waitcnt vmcnt(0)
	v_pk_mul_f32 v[130:131], v[138:139], v[130:131]
	v_pk_mul_f32 v[128:129], v[136:137], v[128:129]
	v_pk_mul_f32 v[126:127], v[126:127], v[172:173] op_sel_hi:[1,0]
	v_pk_mul_f32 v[124:125], v[132:133], v[124:125]
	v_pk_mul_f32 v[126:127], v[134:135], v[126:127]
	v_cvt_pk_bf16_f32 v128, v128, v129
	v_cvt_pk_bf16_f32 v129, v130, v131
	v_cvt_pk_bf16_f32 v130, v124, v125
	v_lshlrev_b64 v[124:125], 13, v[174:175]
	v_cvt_pk_bf16_f32 v131, v126, v127
	v_lshl_add_u64 v[124:125], s[60:61], 0, v[124:125]
	v_lshlrev_b64 v[126:127], 1, v[182:183]
	v_lshl_add_u64 v[124:125], v[124:125], 0, v[126:127]
	global_store_dwordx4 v[124:125], v[128:131], off
	v_pk_mul_f32 v[120:121], v[120:121], v[172:173] op_sel_hi:[1,0]
	v_pk_mul_f32 v[122:123], v[122:123], v[172:173] op_sel_hi:[1,0]
	v_pk_mul_f32 v[128:129], v[116:117], v[172:173] op_sel_hi:[1,0]
	v_add_u32_e32 v116, s10, v163
	v_pk_mul_f32 v[130:131], v[118:119], v[172:173] op_sel_hi:[1,0]
	ds_read_b128 v[116:119], v116
	v_pk_mul_f32 v[122:123], v[146:147], v[122:123]
	v_pk_mul_f32 v[120:121], v[144:145], v[120:121]
	v_pk_mul_f32 v[130:131], v[142:143], v[130:131]
	v_cvt_pk_bf16_f32 v120, v120, v121
	v_cvt_pk_bf16_f32 v121, v122, v123
	s_nop 0
	s_waitcnt lgkmcnt(0)
	v_mov_b32_e32 v122, v117
	v_mov_b32_e32 v123, v118
	v_mov_b32_e32 v117, v119
	v_pk_add_f32 v[116:117], v[122:123], v[116:117]
	v_pk_mul_f32 v[128:129], v[140:141], v[128:129]
	v_add_f32_e32 v116, v116, v117
	v_fmamk_f32 v116, v116, 0x3b800000, v213
	v_rsq_f32_e32 v116, v116
	v_or_b32_e32 v118, 16, v174
	v_cvt_pk_bf16_f32 v122, v128, v129
	v_cvt_pk_bf16_f32 v123, v130, v131
	v_cndmask_b32_e64 v116, 1.0, v116, s[8:9]
	v_mul_f32_e32 v116, v168, v116
	v_pk_mul_f32 v[112:113], v[112:113], v[116:117] op_sel_hi:[1,0]
	v_ashrrev_i32_e32 v119, 31, v118
	v_pk_mul_f32 v[112:113], v[136:137], v[112:113]
	v_pk_mul_f32 v[108:109], v[108:109], v[116:117] op_sel_hi:[1,0]
	v_pk_mul_f32 v[110:111], v[110:111], v[116:117] op_sel_hi:[1,0]
	global_store_dwordx4 v[124:125], v[120:123], off offset:256
	v_pk_mul_f32 v[114:115], v[114:115], v[116:117] op_sel_hi:[1,0]
	v_pk_mul_f32 v[104:105], v[104:105], v[116:117] op_sel_hi:[1,0]
	v_pk_mul_f32 v[120:121], v[134:135], v[110:111]
	v_pk_mul_f32 v[110:111], v[132:133], v[108:109]
	v_cvt_pk_bf16_f32 v108, v112, v113
	v_lshlrev_b64 v[112:113], 13, v[118:119]
	v_pk_mul_f32 v[114:115], v[138:139], v[114:115]
	v_lshl_add_u64 v[112:113], s[60:61], 0, v[112:113]
	v_cvt_pk_bf16_f32 v109, v114, v115
	v_cvt_pk_bf16_f32 v110, v110, v111
	v_cvt_pk_bf16_f32 v111, v120, v121
	v_lshl_add_u64 v[112:113], v[112:113], 0, v[126:127]
	global_store_dwordx4 v[112:113], v[108:111], off
	v_pk_mul_f32 v[106:107], v[106:107], v[116:117] op_sel_hi:[1,0]
	v_pk_mul_f32 v[104:105], v[144:145], v[104:105]
	v_pk_mul_f32 v[108:109], v[100:101], v[116:117] op_sel_hi:[1,0]
	v_add_u32_e32 v100, s10, v165
	v_pk_mul_f32 v[110:111], v[102:103], v[116:117] op_sel_hi:[1,0]
	ds_read_b128 v[100:103], v100
	v_pk_mul_f32 v[106:107], v[146:147], v[106:107]
	v_cvt_pk_bf16_f32 v104, v104, v105
	v_cvt_pk_bf16_f32 v105, v106, v107
	v_pk_mul_f32 v[110:111], v[142:143], v[110:111]
	s_nop 0
	s_waitcnt lgkmcnt(0)
	v_mov_b32_e32 v106, v101
	v_mov_b32_e32 v107, v102
	v_mov_b32_e32 v101, v103
	v_pk_add_f32 v[100:101], v[106:107], v[100:101]
	v_pk_mul_f32 v[108:109], v[140:141], v[108:109]
	v_add_f32_e32 v100, v100, v101
	v_fmamk_f32 v100, v100, 0x3b800000, v213
	v_rsq_f32_e32 v100, v100
	v_or_b32_e32 v102, 32, v174
	v_cvt_pk_bf16_f32 v106, v108, v109
	v_cvt_pk_bf16_f32 v107, v110, v111
	v_cndmask_b32_e64 v100, 1.0, v100, s[8:9]
	v_mul_f32_e32 v100, v170, v100
	v_pk_mul_f32 v[96:97], v[96:97], v[100:101] op_sel_hi:[1,0]
	v_pk_mul_f32 v[92:93], v[92:93], v[100:101] op_sel_hi:[1,0]
	v_ashrrev_i32_e32 v103, 31, v102
	v_pk_mul_f32 v[96:97], v[136:137], v[96:97]
	v_pk_mul_f32 v[94:95], v[94:95], v[100:101] op_sel_hi:[1,0]
	v_pk_mul_f32 v[92:93], v[132:133], v[92:93]
	global_store_dwordx4 v[112:113], v[104:107], off offset:256
	v_pk_mul_f32 v[98:99], v[98:99], v[100:101] op_sel_hi:[1,0]
	v_pk_mul_f32 v[88:89], v[88:89], v[100:101] op_sel_hi:[1,0]
	v_pk_mul_f32 v[104:105], v[134:135], v[94:95]
	v_cvt_pk_bf16_f32 v94, v96, v97
	v_cvt_pk_bf16_f32 v96, v92, v93
	v_lshlrev_b64 v[92:93], 13, v[102:103]
	v_pk_mul_f32 v[98:99], v[138:139], v[98:99]
	v_lshl_add_u64 v[92:93], s[60:61], 0, v[92:93]
	v_cvt_pk_bf16_f32 v95, v98, v99
	v_cvt_pk_bf16_f32 v97, v104, v105
	v_lshl_add_u64 v[92:93], v[92:93], 0, v[126:127]
	global_store_dwordx4 v[92:93], v[94:97], off
	v_pk_mul_f32 v[90:91], v[90:91], v[100:101] op_sel_hi:[1,0]
	v_pk_mul_f32 v[88:89], v[144:145], v[88:89]
	v_pk_mul_f32 v[94:95], v[84:85], v[100:101] op_sel_hi:[1,0]
	v_add_u32_e32 v84, s10, v167
	v_pk_mul_f32 v[96:97], v[86:87], v[100:101] op_sel_hi:[1,0]
	ds_read_b128 v[84:87], v84
	v_pk_mul_f32 v[90:91], v[146:147], v[90:91]
	v_cvt_pk_bf16_f32 v88, v88, v89
	v_cvt_pk_bf16_f32 v89, v90, v91
	v_pk_mul_f32 v[96:97], v[142:143], v[96:97]
	s_nop 0
	s_waitcnt lgkmcnt(0)
	v_mov_b32_e32 v90, v85
	v_mov_b32_e32 v91, v86
	v_mov_b32_e32 v85, v87
	v_pk_add_f32 v[84:85], v[90:91], v[84:85]
	v_pk_mul_f32 v[94:95], v[140:141], v[94:95]
	v_add_f32_e32 v84, v84, v85
	v_fmamk_f32 v84, v84, 0x3b800000, v213
	v_rsq_f32_e32 v84, v84
	v_or_b32_e32 v86, 48, v174
	v_cvt_pk_bf16_f32 v90, v94, v95
	v_cvt_pk_bf16_f32 v91, v96, v97
	v_cndmask_b32_e64 v84, 1.0, v84, s[8:9]
	v_mul_f32_e32 v84, v164, v84
	v_pk_mul_f32 v[80:81], v[80:81], v[84:85] op_sel_hi:[1,0]
	v_ashrrev_i32_e32 v87, 31, v86
	v_pk_mul_f32 v[80:81], v[136:137], v[80:81]
	v_pk_mul_f32 v[76:77], v[76:77], v[84:85] op_sel_hi:[1,0]
	v_pk_mul_f32 v[78:79], v[78:79], v[84:85] op_sel_hi:[1,0]
	global_store_dwordx4 v[92:93], v[88:91], off offset:256
	v_pk_mul_f32 v[82:83], v[82:83], v[84:85] op_sel_hi:[1,0]
	v_pk_mul_f32 v[72:73], v[72:73], v[84:85] op_sel_hi:[1,0]
	v_pk_mul_f32 v[88:89], v[134:135], v[78:79]
	v_pk_mul_f32 v[78:79], v[132:133], v[76:77]
	v_cvt_pk_bf16_f32 v76, v80, v81
	v_lshlrev_b64 v[80:81], 13, v[86:87]
	v_pk_mul_f32 v[82:83], v[138:139], v[82:83]
	v_lshl_add_u64 v[80:81], s[60:61], 0, v[80:81]
	v_cvt_pk_bf16_f32 v77, v82, v83
	v_cvt_pk_bf16_f32 v78, v78, v79
	v_cvt_pk_bf16_f32 v79, v88, v89
	v_lshl_add_u64 v[80:81], v[80:81], 0, v[126:127]
	global_store_dwordx4 v[80:81], v[76:79], off
	v_pk_mul_f32 v[74:75], v[74:75], v[84:85] op_sel_hi:[1,0]
	v_pk_mul_f32 v[72:73], v[144:145], v[72:73]
	v_pk_mul_f32 v[76:77], v[68:69], v[84:85] op_sel_hi:[1,0]
	v_add_u32_e32 v68, s10, v169
	v_pk_mul_f32 v[78:79], v[70:71], v[84:85] op_sel_hi:[1,0]
	ds_read_b128 v[68:71], v68
	v_pk_mul_f32 v[74:75], v[146:147], v[74:75]
	v_cvt_pk_bf16_f32 v72, v72, v73
	v_cvt_pk_bf16_f32 v73, v74, v75
	v_pk_mul_f32 v[78:79], v[142:143], v[78:79]
	s_nop 0
	s_waitcnt lgkmcnt(0)
	v_mov_b32_e32 v74, v69
	v_mov_b32_e32 v75, v70
	v_mov_b32_e32 v69, v71
	v_pk_add_f32 v[68:69], v[74:75], v[68:69]
	v_pk_mul_f32 v[76:77], v[140:141], v[76:77]
	v_add_f32_e32 v68, v68, v69
	v_fmamk_f32 v68, v68, 0x3b800000, v213
	v_rsq_f32_e32 v68, v68
	v_cvt_pk_bf16_f32 v74, v76, v77
	v_cvt_pk_bf16_f32 v75, v78, v79
	global_store_dwordx4 v[80:81], v[72:75], off offset:256
	v_cndmask_b32_e64 v68, 1.0, v68, s[8:9]
	v_mul_f32_e32 v68, v166, v68
	v_pk_mul_f32 v[66:67], v[66:67], v[68:69] op_sel_hi:[1,0]
	v_pk_mul_f32 v[64:65], v[64:65], v[68:69] op_sel_hi:[1,0]
	v_pk_mul_f32 v[66:67], v[138:139], v[66:67]
	v_pk_mul_f32 v[60:61], v[60:61], v[68:69] op_sel_hi:[1,0]
	v_pk_mul_f32 v[62:63], v[62:63], v[68:69] op_sel_hi:[1,0]
	v_pk_mul_f32 v[64:65], v[136:137], v[64:65]
	v_pk_mul_f32 v[70:71], v[134:135], v[62:63]
	v_pk_mul_f32 v[60:61], v[132:133], v[60:61]
	v_cvt_pk_bf16_f32 v63, v66, v67
	v_add_co_u32_e32 v66, vcc, s11, v124
	v_cvt_pk_bf16_f32 v62, v64, v65
	v_cvt_pk_bf16_f32 v64, v60, v61
	v_cvt_pk_bf16_f32 v65, v70, v71
	v_addc_co_u32_e32 v67, vcc, 0, v125, vcc
	global_store_dwordx4 v[66:67], v[62:65], off
	v_pk_mul_f32 v[56:57], v[56:57], v[68:69] op_sel_hi:[1,0]
	v_pk_mul_f32 v[58:59], v[58:59], v[68:69] op_sel_hi:[1,0]
	v_pk_mul_f32 v[62:63], v[52:53], v[68:69] op_sel_hi:[1,0]
	v_add_u32_e32 v52, s10, v171
	v_pk_mul_f32 v[64:65], v[54:55], v[68:69] op_sel_hi:[1,0]
	ds_read_b128 v[52:55], v52
	v_pk_mul_f32 v[58:59], v[146:147], v[58:59]
	v_pk_mul_f32 v[56:57], v[144:145], v[56:57]
	s_mov_b32 s11, 0x120000
	v_cvt_pk_bf16_f32 v56, v56, v57
	v_cvt_pk_bf16_f32 v57, v58, v59
	s_nop 0
	s_waitcnt lgkmcnt(0)
	v_mov_b32_e32 v58, v53
	v_mov_b32_e32 v59, v54
	v_mov_b32_e32 v53, v55
	v_pk_add_f32 v[52:53], v[58:59], v[52:53]
	v_lshl_add_u64 v[60:61], v[124:125], 0, s[40:41]
	v_add_f32_e32 v52, v52, v53
	v_fmamk_f32 v52, v52, 0x3b800000, v213
	v_rsq_f32_e32 v52, v52
	s_mov_b64 s[40:41], 0x120000
	v_pk_mul_f32 v[64:65], v[142:143], v[64:65]
	v_pk_mul_f32 v[62:63], v[140:141], v[62:63]
	v_cndmask_b32_e64 v52, 1.0, v52, s[8:9]
	v_mul_f32_e32 v52, v160, v52
	v_pk_mul_f32 v[50:51], v[50:51], v[52:53] op_sel_hi:[1,0]
	v_pk_mul_f32 v[48:49], v[48:49], v[52:53] op_sel_hi:[1,0]
	v_pk_mul_f32 v[50:51], v[138:139], v[50:51]
	v_pk_mul_f32 v[44:45], v[44:45], v[52:53] op_sel_hi:[1,0]
	v_pk_mul_f32 v[46:47], v[46:47], v[52:53] op_sel_hi:[1,0]
	v_pk_mul_f32 v[48:49], v[136:137], v[48:49]
	v_pk_mul_f32 v[54:55], v[134:135], v[46:47]
	v_pk_mul_f32 v[46:47], v[132:133], v[44:45]
	v_cvt_pk_bf16_f32 v45, v50, v51
	v_add_co_u32_e32 v50, vcc, s11, v124
	v_cvt_pk_bf16_f32 v44, v48, v49
	v_cvt_pk_bf16_f32 v46, v46, v47
	v_cvt_pk_bf16_f32 v47, v54, v55
	v_addc_co_u32_e32 v51, vcc, 0, v125, vcc
	global_store_dwordx4 v[50:51], v[44:47], off
	v_pk_mul_f32 v[40:41], v[40:41], v[52:53] op_sel_hi:[1,0]
	v_pk_mul_f32 v[42:43], v[42:43], v[52:53] op_sel_hi:[1,0]
	v_pk_mul_f32 v[44:45], v[36:37], v[52:53] op_sel_hi:[1,0]
	v_add_u32_e32 v36, s10, v173
	v_pk_mul_f32 v[46:47], v[38:39], v[52:53] op_sel_hi:[1,0]
	ds_read_b128 v[36:39], v36
	v_pk_mul_f32 v[42:43], v[146:147], v[42:43]
	v_pk_mul_f32 v[40:41], v[144:145], v[40:41]
	s_mov_b32 s11, 0x140000
	v_cvt_pk_bf16_f32 v40, v40, v41
	v_cvt_pk_bf16_f32 v41, v42, v43
	s_nop 0
	s_waitcnt lgkmcnt(0)
	v_mov_b32_e32 v42, v37
	v_mov_b32_e32 v43, v38
	v_mov_b32_e32 v37, v39
	v_pk_add_f32 v[36:37], v[42:43], v[36:37]
	v_lshl_add_u64 v[48:49], v[124:125], 0, s[40:41]
	v_add_f32_e32 v36, v36, v37
	v_fmamk_f32 v36, v36, 0x3b800000, v213
	v_rsq_f32_e32 v36, v36
	v_pk_mul_f32 v[46:47], v[142:143], v[46:47]
	v_pk_mul_f32 v[44:45], v[140:141], v[44:45]
	s_mov_b64 s[40:41], 0x140000
	v_cndmask_b32_e64 v36, 1.0, v36, s[8:9]
	v_mul_f32_e32 v36, v162, v36
	v_pk_mul_f32 v[34:35], v[34:35], v[36:37] op_sel_hi:[1,0]
	v_pk_mul_f32 v[32:33], v[32:33], v[36:37] op_sel_hi:[1,0]
	v_pk_mul_f32 v[34:35], v[138:139], v[34:35]
	v_pk_mul_f32 v[28:29], v[28:29], v[36:37] op_sel_hi:[1,0]
	v_pk_mul_f32 v[30:31], v[30:31], v[36:37] op_sel_hi:[1,0]
	v_pk_mul_f32 v[32:33], v[136:137], v[32:33]
	v_pk_mul_f32 v[38:39], v[134:135], v[30:31]
	v_pk_mul_f32 v[28:29], v[132:133], v[28:29]
	v_cvt_pk_bf16_f32 v31, v34, v35
	v_add_co_u32_e32 v34, vcc, s11, v124
	v_cvt_pk_bf16_f32 v30, v32, v33
	v_cvt_pk_bf16_f32 v32, v28, v29
	v_cvt_pk_bf16_f32 v33, v38, v39
	v_addc_co_u32_e32 v35, vcc, 0, v125, vcc
	global_store_dwordx4 v[34:35], v[30:33], off
	v_pk_mul_f32 v[24:25], v[24:25], v[36:37] op_sel_hi:[1,0]
	v_pk_mul_f32 v[26:27], v[26:27], v[36:37] op_sel_hi:[1,0]
	v_pk_mul_f32 v[30:31], v[20:21], v[36:37] op_sel_hi:[1,0]
	v_add_u32_e32 v20, s10, v176
	v_pk_mul_f32 v[32:33], v[22:23], v[36:37] op_sel_hi:[1,0]
	ds_read_b128 v[20:23], v20
	v_pk_mul_f32 v[26:27], v[146:147], v[26:27]
	v_pk_mul_f32 v[24:25], v[144:145], v[24:25]
	v_pk_mul_f32 v[32:33], v[142:143], v[32:33]
	v_cvt_pk_bf16_f32 v24, v24, v25
	v_cvt_pk_bf16_f32 v25, v26, v27
	s_nop 0
	s_waitcnt lgkmcnt(0)
	v_mov_b32_e32 v26, v21
	v_mov_b32_e32 v27, v22
	v_mov_b32_e32 v21, v23
	v_pk_add_f32 v[20:21], v[26:27], v[20:21]
	v_pk_mul_f32 v[30:31], v[140:141], v[30:31]
	v_add_f32_e32 v20, v20, v21
	v_fmamk_f32 v20, v20, 0x3b800000, v213
	v_rsq_f32_e32 v20, v20
	v_cvt_pk_bf16_f32 v58, v62, v63
	v_cvt_pk_bf16_f32 v59, v64, v65
	v_cvt_pk_bf16_f32 v42, v44, v45
	v_cndmask_b32_e64 v20, 1.0, v20, s[8:9]
	v_mul_f32_e32 v20, v158, v20
	v_pk_mul_f32 v[16:17], v[16:17], v[20:21] op_sel_hi:[1,0]
	v_pk_mul_f32 v[18:19], v[18:19], v[20:21] op_sel_hi:[1,0]
	v_pk_mul_f32 v[16:17], v[136:137], v[16:17]
	v_pk_mul_f32 v[12:13], v[12:13], v[20:21] op_sel_hi:[1,0]
	v_pk_mul_f32 v[14:15], v[14:15], v[20:21] op_sel_hi:[1,0]
	s_mov_b64 s[8:9], 0x160000
	v_pk_mul_f32 v[18:19], v[138:139], v[18:19]
	v_pk_mul_f32 v[22:23], v[134:135], v[14:15]
	v_pk_mul_f32 v[14:15], v[132:133], v[12:13]
	v_cvt_pk_bf16_f32 v12, v16, v17
	v_lshl_add_u64 v[16:17], v[124:125], 0, s[8:9]
	s_mov_b32 s8, 0x160000
	v_cvt_pk_bf16_f32 v13, v18, v19
	v_add_co_u32_e32 v18, vcc, s8, v124
	v_cvt_pk_bf16_f32 v14, v14, v15
	v_cvt_pk_bf16_f32 v15, v22, v23
	v_addc_co_u32_e32 v19, vcc, 0, v125, vcc
	v_pk_mul_f32 v[8:9], v[8:9], v[20:21] op_sel_hi:[1,0]
	v_pk_mul_f32 v[10:11], v[10:11], v[20:21] op_sel_hi:[1,0]
	v_pk_mul_f32 v[4:5], v[4:5], v[20:21] op_sel_hi:[1,0]
	v_pk_mul_f32 v[6:7], v[6:7], v[20:21] op_sel_hi:[1,0]
	global_store_dwordx4 v[18:19], v[12:15], off
	v_pk_mul_f32 v[10:11], v[146:147], v[10:11]
	v_pk_mul_f32 v[8:9], v[144:145], v[8:9]
	v_pk_mul_f32 v[12:13], v[142:143], v[6:7]
	v_pk_mul_f32 v[6:7], v[140:141], v[4:5]
	v_cvt_pk_bf16_f32 v43, v46, v47
	v_lshl_add_u64 v[28:29], v[124:125], 0, s[40:41]
	v_cvt_pk_bf16_f32 v26, v30, v31
	v_cvt_pk_bf16_f32 v27, v32, v33
	v_cvt_pk_bf16_f32 v4, v8, v9
	v_cvt_pk_bf16_f32 v5, v10, v11
	v_cvt_pk_bf16_f32 v6, v6, v7
	v_cvt_pk_bf16_f32 v7, v12, v13
	s_waitcnt lgkmcnt(0)
	s_andn2_b64 vcc, exec, s[36:37]
	s_mov_b64 s[8:9], -1
	global_store_dwordx4 v[60:61], v[56:59], off offset:256
	global_store_dwordx4 v[48:49], v[40:43], off offset:256
	global_store_dwordx4 v[28:29], v[24:27], off offset:256
	global_store_dwordx4 v[16:17], v[4:7], off offset:256
	s_cbranch_vccnz .LBB0_74
	s_andn2_b64 vcc, exec, s[14:15]
	s_cbranch_vccnz .LBB0_73
	s_barrier
	s_branch .LBB0_73

.LBB0_145:
	s_lshl_b32 s15, s58, 10
	s_and_b32 s15, s15, 0x1c00
	v_add_u32_e32 v151, s15, v141
	ds_read2_b32 v[146:147], v151 offset1:16
	v_lshl_or_b32 v144, s59, 8, v142
	v_lshl_add_u32 v150, s58, 8, v3
	v_ashrrev_i32_e32 v145, 31, v144
	s_movk_i32 s15, 0x1c00
	s_waitcnt lgkmcnt(0)
	v_pk_mul_f32 v[130:131], v[130:131], v[146:147] op_sel_hi:[1,0]
	v_pk_mul_f32 v[128:129], v[128:129], v[146:147] op_sel_hi:[1,0]
	v_pk_mul_f32 v[124:125], v[124:125], v[146:147] op_sel_hi:[1,0]
	v_pk_mul_f32 v[126:127], v[126:127], v[146:147] op_sel_hi:[1,0]
	v_cvt_pk_bf16_f32 v128, v128, v129
	v_cvt_pk_bf16_f32 v129, v130, v131
	v_cvt_pk_bf16_f32 v130, v124, v125
	v_mov_b64_e32 v[124:125], s[4:5]
	v_cvt_pk_bf16_f32 v131, v126, v127
	v_mad_i64_i32 v[148:149], s[36:37], v150, s15, v[124:125]
	v_lshlrev_b64 v[126:127], 1, v[144:145]
	v_lshl_add_u64 v[144:145], v[148:149], 0, v[126:127]
	global_store_dwordx4 v[144:145], v[128:131], off
	v_pk_mul_f32 v[118:119], v[118:119], v[146:147] op_sel_hi:[1,0]
	v_pk_mul_f32 v[116:117], v[116:117], v[146:147] op_sel_hi:[1,0]
	v_pk_mul_f32 v[128:129], v[110:111], v[146:147] op_sel_hi:[1,0]
	v_pk_mul_f32 v[110:111], v[108:109], v[146:147] op_sel_hi:[1,0]
	v_cvt_pk_bf16_f32 v108, v116, v117
	v_cvt_pk_bf16_f32 v109, v118, v119
	v_cvt_pk_bf16_f32 v110, v110, v111
	v_cvt_pk_bf16_f32 v111, v128, v129
	v_or_b32_e32 v117, 16, v150
	v_mov_b32_e32 v116, v147
	global_store_dwordx4 v[144:145], v[108:111], off offset:256
	v_pk_mul_f32 v[112:113], v[112:113], v[116:117] op_sel_hi:[1,0]
	v_pk_mul_f32 v[114:115], v[114:115], v[116:117] op_sel_hi:[1,0]
	v_pk_mul_f32 v[110:111], v[122:123], v[116:117] op_sel_hi:[1,0]
	v_pk_mul_f32 v[108:109], v[120:121], v[116:117] op_sel_hi:[1,0]
	v_pk_mul_f32 v[106:107], v[106:107], v[116:117] op_sel_hi:[1,0]
	v_cvt_pk_bf16_f32 v108, v108, v109
	v_cvt_pk_bf16_f32 v109, v110, v111
	v_cvt_pk_bf16_f32 v110, v112, v113
	v_mad_i64_i32 v[112:113], s[36:37], v117, s15, v[124:125]
	v_cvt_pk_bf16_f32 v111, v114, v115
	v_lshl_add_u64 v[112:113], v[112:113], 0, v[126:127]
	global_store_dwordx4 v[112:113], v[108:111], off
	v_pk_mul_f32 v[104:105], v[104:105], v[116:117] op_sel_hi:[1,0]
	s_andn2_b64 vcc, exec, s[6:7]
	ds_read2_b32 v[110:111], v151 offset0:32 offset1:48
	ds_read2_b32 v[114:115], v151 offset0:128 offset1:144
	ds_read2_b32 v[118:119], v151 offset0:160 offset1:176
	v_pk_mul_f32 v[108:109], v[102:103], v[116:117] op_sel_hi:[1,0]
	v_pk_mul_f32 v[102:103], v[100:101], v[116:117] op_sel_hi:[1,0]
	v_cvt_pk_bf16_f32 v100, v104, v105
	v_cvt_pk_bf16_f32 v101, v106, v107
	v_cvt_pk_bf16_f32 v102, v102, v103
	v_cvt_pk_bf16_f32 v103, v108, v109
	global_store_dwordx4 v[112:113], v[100:103], off offset:256
	s_nop 0
	v_or_b32_e32 v104, 32, v150
	s_nop 0
	s_waitcnt lgkmcnt(2)
	v_pk_mul_f32 v[96:97], v[96:97], v[110:111] op_sel_hi:[1,0]
	v_pk_mul_f32 v[98:99], v[98:99], v[110:111] op_sel_hi:[1,0]
	v_pk_mul_f32 v[102:103], v[94:95], v[110:111] op_sel_hi:[1,0]
	v_pk_mul_f32 v[94:95], v[92:93], v[110:111] op_sel_hi:[1,0]
	v_cvt_pk_bf16_f32 v92, v96, v97
	v_mad_i64_i32 v[96:97], s[36:37], v104, s15, v[124:125]
	v_cvt_pk_bf16_f32 v93, v98, v99
	v_cvt_pk_bf16_f32 v94, v94, v95
	v_cvt_pk_bf16_f32 v95, v102, v103
	v_lshl_add_u64 v[96:97], v[96:97], 0, v[126:127]
	global_store_dwordx4 v[96:97], v[92:95], off
	v_pk_mul_f32 v[86:87], v[86:87], v[110:111] op_sel_hi:[1,0]
	v_pk_mul_f32 v[84:85], v[84:85], v[110:111] op_sel_hi:[1,0]
	v_pk_mul_f32 v[92:93], v[78:79], v[110:111] op_sel_hi:[1,0]
	v_pk_mul_f32 v[78:79], v[76:77], v[110:111] op_sel_hi:[1,0]
	v_cvt_pk_bf16_f32 v76, v84, v85
	v_cvt_pk_bf16_f32 v77, v86, v87
	v_cvt_pk_bf16_f32 v78, v78, v79
	v_cvt_pk_bf16_f32 v79, v92, v93
	v_or_b32_e32 v85, 48, v150
	v_mov_b32_e32 v84, v111
	global_store_dwordx4 v[96:97], v[76:79], off offset:256
	v_pk_mul_f32 v[80:81], v[80:81], v[84:85] op_sel_hi:[1,0]
	v_pk_mul_f32 v[82:83], v[82:83], v[84:85] op_sel_hi:[1,0]
	v_pk_mul_f32 v[78:79], v[90:91], v[84:85] op_sel_hi:[1,0]
	v_pk_mul_f32 v[76:77], v[88:89], v[84:85] op_sel_hi:[1,0]
	v_pk_mul_f32 v[74:75], v[74:75], v[84:85] op_sel_hi:[1,0]
	v_cvt_pk_bf16_f32 v76, v76, v77
	v_cvt_pk_bf16_f32 v77, v78, v79
	v_cvt_pk_bf16_f32 v78, v80, v81
	v_mad_i64_i32 v[80:81], s[36:37], v85, s15, v[124:125]
	v_cvt_pk_bf16_f32 v79, v82, v83
	v_lshl_add_u64 v[80:81], v[80:81], 0, v[126:127]
	global_store_dwordx4 v[80:81], v[76:79], off
	v_pk_mul_f32 v[72:73], v[72:73], v[84:85] op_sel_hi:[1,0]
	s_nop 0
	v_pk_mul_f32 v[76:77], v[70:71], v[84:85] op_sel_hi:[1,0]
	v_pk_mul_f32 v[70:71], v[68:69], v[84:85] op_sel_hi:[1,0]
	v_cvt_pk_bf16_f32 v68, v72, v73
	v_cvt_pk_bf16_f32 v69, v74, v75
	v_cvt_pk_bf16_f32 v70, v70, v71
	v_cvt_pk_bf16_f32 v71, v76, v77
	global_store_dwordx4 v[80:81], v[68:71], off offset:256
	s_nop 0
	v_add_u32_e32 v72, 0x80, v150
	s_nop 0
	s_waitcnt lgkmcnt(1)
	v_pk_mul_f32 v[64:65], v[64:65], v[114:115] op_sel_hi:[1,0]
	v_pk_mul_f32 v[66:67], v[66:67], v[114:115] op_sel_hi:[1,0]
	v_pk_mul_f32 v[70:71], v[62:63], v[114:115] op_sel_hi:[1,0]
	v_pk_mul_f32 v[62:63], v[60:61], v[114:115] op_sel_hi:[1,0]
	v_cvt_pk_bf16_f32 v60, v64, v65
	v_mad_i64_i32 v[64:65], s[36:37], v72, s15, v[124:125]
	v_cvt_pk_bf16_f32 v61, v66, v67
	v_cvt_pk_bf16_f32 v62, v62, v63
	v_cvt_pk_bf16_f32 v63, v70, v71
	v_lshl_add_u64 v[64:65], v[64:65], 0, v[126:127]
	global_store_dwordx4 v[64:65], v[60:63], off
	v_pk_mul_f32 v[54:55], v[54:55], v[114:115] op_sel_hi:[1,0]
	v_pk_mul_f32 v[52:53], v[52:53], v[114:115] op_sel_hi:[1,0]
	v_pk_mul_f32 v[60:61], v[46:47], v[114:115] op_sel_hi:[1,0]
	v_pk_mul_f32 v[46:47], v[44:45], v[114:115] op_sel_hi:[1,0]
	v_cvt_pk_bf16_f32 v44, v52, v53
	v_cvt_pk_bf16_f32 v45, v54, v55
	v_cvt_pk_bf16_f32 v46, v46, v47
	v_cvt_pk_bf16_f32 v47, v60, v61
	v_add_u32_e32 v53, 0x90, v150
	v_mov_b32_e32 v52, v115
	global_store_dwordx4 v[64:65], v[44:47], off offset:256
	v_pk_mul_f32 v[48:49], v[48:49], v[52:53] op_sel_hi:[1,0]
	v_pk_mul_f32 v[50:51], v[50:51], v[52:53] op_sel_hi:[1,0]
	v_pk_mul_f32 v[46:47], v[58:59], v[52:53] op_sel_hi:[1,0]
	v_pk_mul_f32 v[44:45], v[56:57], v[52:53] op_sel_hi:[1,0]
	v_pk_mul_f32 v[42:43], v[42:43], v[52:53] op_sel_hi:[1,0]
	v_cvt_pk_bf16_f32 v44, v44, v45
	v_cvt_pk_bf16_f32 v45, v46, v47
	v_cvt_pk_bf16_f32 v46, v48, v49
	v_mad_i64_i32 v[48:49], s[36:37], v53, s15, v[124:125]
	v_cvt_pk_bf16_f32 v47, v50, v51
	v_lshl_add_u64 v[48:49], v[48:49], 0, v[126:127]
	global_store_dwordx4 v[48:49], v[44:47], off
	v_pk_mul_f32 v[40:41], v[40:41], v[52:53] op_sel_hi:[1,0]
	s_nop 0
	v_pk_mul_f32 v[44:45], v[38:39], v[52:53] op_sel_hi:[1,0]
	v_pk_mul_f32 v[38:39], v[36:37], v[52:53] op_sel_hi:[1,0]
	v_cvt_pk_bf16_f32 v36, v40, v41
	v_cvt_pk_bf16_f32 v37, v42, v43
	v_cvt_pk_bf16_f32 v38, v38, v39
	v_cvt_pk_bf16_f32 v39, v44, v45
	global_store_dwordx4 v[48:49], v[36:39], off offset:256
	s_nop 0
	v_add_u32_e32 v40, 0xa0, v150
	s_nop 0
	s_waitcnt lgkmcnt(0)
	v_pk_mul_f32 v[32:33], v[32:33], v[118:119] op_sel_hi:[1,0]
	v_pk_mul_f32 v[34:35], v[34:35], v[118:119] op_sel_hi:[1,0]
	v_pk_mul_f32 v[38:39], v[30:31], v[118:119] op_sel_hi:[1,0]
	v_pk_mul_f32 v[30:31], v[28:29], v[118:119] op_sel_hi:[1,0]
	v_cvt_pk_bf16_f32 v28, v32, v33
	v_mad_i64_i32 v[32:33], s[36:37], v40, s15, v[124:125]
	v_cvt_pk_bf16_f32 v29, v34, v35
	v_cvt_pk_bf16_f32 v30, v30, v31
	v_cvt_pk_bf16_f32 v31, v38, v39
	v_lshl_add_u64 v[32:33], v[32:33], 0, v[126:127]
	global_store_dwordx4 v[32:33], v[28:31], off
	v_pk_mul_f32 v[22:23], v[22:23], v[118:119] op_sel_hi:[1,0]
	v_pk_mul_f32 v[20:21], v[20:21], v[118:119] op_sel_hi:[1,0]
	v_pk_mul_f32 v[28:29], v[14:15], v[118:119] op_sel_hi:[1,0]
	v_pk_mul_f32 v[14:15], v[12:13], v[118:119] op_sel_hi:[1,0]
	v_cvt_pk_bf16_f32 v12, v20, v21
	v_cvt_pk_bf16_f32 v13, v22, v23
	v_cvt_pk_bf16_f32 v14, v14, v15
	v_cvt_pk_bf16_f32 v15, v28, v29
	v_add_u32_e32 v21, 0xb0, v150
	v_mov_b32_e32 v20, v119
	global_store_dwordx4 v[32:33], v[12:15], off offset:256
	v_pk_mul_f32 v[16:17], v[16:17], v[20:21] op_sel_hi:[1,0]
	v_pk_mul_f32 v[18:19], v[18:19], v[20:21] op_sel_hi:[1,0]
	v_pk_mul_f32 v[14:15], v[26:27], v[20:21] op_sel_hi:[1,0]
	v_pk_mul_f32 v[12:13], v[24:25], v[20:21] op_sel_hi:[1,0]
	v_pk_mul_f32 v[10:11], v[10:11], v[20:21] op_sel_hi:[1,0]
	v_cvt_pk_bf16_f32 v12, v12, v13
	v_cvt_pk_bf16_f32 v13, v14, v15
	v_cvt_pk_bf16_f32 v14, v16, v17
	v_mad_i64_i32 v[16:17], s[36:37], v21, s15, v[124:125]
	v_cvt_pk_bf16_f32 v15, v18, v19
	v_lshl_add_u64 v[16:17], v[16:17], 0, v[126:127]
	global_store_dwordx4 v[16:17], v[12:15], off
	v_pk_mul_f32 v[8:9], v[8:9], v[20:21] op_sel_hi:[1,0]
	s_mov_b64 s[36:37], -1
	v_pk_mul_f32 v[12:13], v[6:7], v[20:21] op_sel_hi:[1,0]
	v_pk_mul_f32 v[6:7], v[4:5], v[20:21] op_sel_hi:[1,0]
	v_cvt_pk_bf16_f32 v4, v8, v9
	v_cvt_pk_bf16_f32 v5, v10, v11
	v_cvt_pk_bf16_f32 v6, v6, v7
	v_cvt_pk_bf16_f32 v7, v12, v13
	global_store_dwordx4 v[16:17], v[4:7], off offset:256
	s_waitcnt lgkmcnt(0)
	s_cbranch_vccnz .LBB0_138
	s_andn2_b64 vcc, exec, s[8:9]
	s_cbranch_vccnz .LBB0_137
	s_barrier
	s_branch .LBB0_137
